# mem-attention task prologue: 8 serialized K/V staging loads + 4 Q loads issued up front with counted vmcnt (on top of attention epilogue hoist)
# baseline (speedup 1.0000x reference)
.LBB0_176:
	s_ashr_i32 s11, s10, 6
	s_lshl_b32 s12, s11, 8
	s_ashr_i32 s13, s12, 31
	s_lshl_b64 s[12:13], s[12:13], 12
	s_add_u32 s12, s6, s12
	s_addc_u32 s13, s7, s13
	s_and_b32 s4, s8, 0xc0
	s_lshl_b32 s4, s4, 1
	s_add_u32 s12, s12, s4
	s_addc_u32 s13, s13, 0
	v_lshl_add_u64 v[4:5], s[12:13], 0, v[160:161]
	v_lshl_add_u64 v[6:7], v[4:5], 0, v[140:141]
	global_load_dwordx4 v[44:47], v[6:7], off offset:512
	v_lshl_add_u64 v[8:9], v[4:5], 0, v[142:143]
	v_lshl_add_u64 v[10:11], v[4:5], 0, v[144:145]
	v_lshl_add_u64 v[4:5], v[4:5], 0, v[146:147]
	s_lshl_b32 s11, s11, 12
	s_and_b32 s12, s9, 0xf00
	s_or_b32 s11, s11, s12
	v_mov_b32_e32 v149, v161
	v_add_u32_e32 v12, v159, v167
	s_add_i32 s10, s10, s33
	s_add_i32 s8, s8, s91
	s_add_i32 s9, s9, s92
	s_cmpk_lt_i32 s10, 0x100
	global_load_dwordx4 v[16:19], v[8:9], off offset:512
	global_load_dwordx4 v[20:23], v[10:11], off offset:512
	global_load_dwordx4 v[24:27], v[4:5], off offset:512
	global_load_dwordx4 v[28:31], v[6:7], off
	global_load_dwordx4 v[32:35], v[8:9], off
	global_load_dwordx4 v[36:39], v[10:11], off
	global_load_dwordx4 v[40:43], v[4:5], off
	v_add_u32_e32 v0, s11, v158
	v_ashrrev_i32_e32 v1, 31, v0
	v_lshlrev_b64 v[152:153], 11, v[0:1]
	v_lshl_add_u64 v[0:1], s[64:65], 0, v[152:153]
	v_lshl_add_u64 v[0:1], v[0:1], 0, s[4:5]
	v_lshl_add_u64 v[4:5], v[0:1], 0, v[148:149]
	global_load_dwordx4 v[0:3], v[4:5], off offset:1536
	global_load_dwordx4 v[136:139], v[4:5], off offset:1568
	global_load_dwordx4 v[132:135], v[4:5], off offset:1600
	global_load_dwordx4 v[128:131], v[4:5], off offset:1632
	s_waitcnt vmcnt(11)
	ds_write_b16 v154, v44
	ds_write_b16_d16_hi v154, v44 offset:520
	ds_write_b16 v154, v45 offset:1040
	ds_write_b16_d16_hi v154, v45 offset:1560
	ds_write_b16 v154, v46 offset:2080
	ds_write_b16_d16_hi v154, v46 offset:2600
	ds_write_b16 v154, v47 offset:3120
	ds_write_b16_d16_hi v154, v47 offset:3640
	s_waitcnt vmcnt(10)
	ds_write_b16 v155, v16
	ds_write_b16_d16_hi v155, v16 offset:520
	ds_write_b16 v155, v17 offset:1040
	ds_write_b16_d16_hi v155, v17 offset:1560
	ds_write_b16 v155, v18 offset:2080
	ds_write_b16_d16_hi v155, v18 offset:2600
	ds_write_b16 v155, v19 offset:3120
	ds_write_b16_d16_hi v155, v19 offset:3640
	s_waitcnt vmcnt(9)
	ds_write_b16 v156, v20
	ds_write_b16_d16_hi v156, v20 offset:520
	ds_write_b16 v156, v21 offset:1040
	ds_write_b16_d16_hi v156, v21 offset:1560
	ds_write_b16 v156, v22 offset:2080
	ds_write_b16_d16_hi v156, v22 offset:2600
	ds_write_b16 v156, v23 offset:3120
	ds_write_b16_d16_hi v156, v23 offset:3640
	s_waitcnt vmcnt(8)
	ds_write_b16 v157, v24
	ds_write_b16_d16_hi v157, v24 offset:520
	ds_write_b16 v157, v25 offset:1040
	ds_write_b16_d16_hi v157, v25 offset:1560
	ds_write_b16 v157, v26 offset:2080
	ds_write_b16_d16_hi v157, v26 offset:2600
	ds_write_b16 v157, v27 offset:3120
	ds_write_b16_d16_hi v157, v27 offset:3640
	s_waitcnt vmcnt(7)
	ds_write_b128 v171, v[28:31] offset:33280
	s_waitcnt vmcnt(6)
	ds_write_b128 v172, v[32:35] offset:33280
	s_waitcnt vmcnt(5)
	ds_write_b128 v173, v[36:39] offset:33280
	s_waitcnt vmcnt(4)
	ds_write_b128 v174, v[40:43] offset:33280
	s_waitcnt lgkmcnt(0)
	s_barrier
	ds_read_b128 v[4:7], v12 offset:33280
	ds_read_b128 v[8:11], v12 offset:33312
	s_waitcnt vmcnt(3) lgkmcnt(1)
	v_mfma_f32_32x32x16_bf16 v[112:127], v[4:7], v[0:3], 0
	ds_read_b128 v[4:7], v12 offset:33344
	s_waitcnt vmcnt(2) lgkmcnt(1)
	v_mfma_f32_32x32x16_bf16 v[112:127], v[8:11], v[136:139], v[112:127]
	s_waitcnt vmcnt(1) lgkmcnt(0)
	v_mfma_f32_32x32x16_bf16 v[112:127], v[4:7], v[132:135], v[112:127]
	ds_read_b128 v[4:7], v12 offset:33376
	s_waitcnt vmcnt(0) lgkmcnt(0)
	v_mfma_f32_32x32x16_bf16 v[112:127], v[4:7], v[128:131], v[112:127]
	ds_read_b128 v[4:7], v12 offset:37888
	s_waitcnt lgkmcnt(0)
	v_mfma_f32_32x32x16_bf16 v[96:111], v[4:7], v[0:3], 0
	ds_read_b128 v[4:7], v12 offset:37920
	s_waitcnt lgkmcnt(0)
	v_mfma_f32_32x32x16_bf16 v[96:111], v[4:7], v[136:139], v[96:111]
	ds_read_b128 v[4:7], v12 offset:37952
	s_waitcnt lgkmcnt(0)
	v_mfma_f32_32x32x16_bf16 v[96:111], v[4:7], v[132:135], v[96:111]
	ds_read_b128 v[4:7], v12 offset:37984
	s_waitcnt lgkmcnt(0)
	v_mfma_f32_32x32x16_bf16 v[96:111], v[4:7], v[128:131], v[96:111]
	ds_read_b128 v[4:7], v12 offset:42496
	s_waitcnt lgkmcnt(0)
	v_mfma_f32_32x32x16_bf16 v[80:95], v[4:7], v[0:3], 0
	ds_read_b128 v[4:7], v12 offset:42528
	s_waitcnt lgkmcnt(0)
	v_mfma_f32_32x32x16_bf16 v[80:95], v[4:7], v[136:139], v[80:95]
	ds_read_b128 v[4:7], v12 offset:42560
	s_waitcnt lgkmcnt(0)
	v_mfma_f32_32x32x16_bf16 v[80:95], v[4:7], v[132:135], v[80:95]
	ds_read_b128 v[4:7], v12 offset:42592
	s_waitcnt lgkmcnt(0)
	v_mfma_f32_32x32x16_bf16 v[80:95], v[4:7], v[128:131], v[80:95]
	ds_read_b128 v[4:7], v12 offset:47104
	s_waitcnt lgkmcnt(0)
	v_mfma_f32_32x32x16_bf16 v[64:79], v[4:7], v[0:3], 0
	ds_read_b128 v[4:7], v12 offset:47136
	s_waitcnt lgkmcnt(0)
	v_mfma_f32_32x32x16_bf16 v[64:79], v[4:7], v[136:139], v[64:79]
	ds_read_b128 v[4:7], v12 offset:47168
	s_waitcnt lgkmcnt(0)
	v_mfma_f32_32x32x16_bf16 v[64:79], v[4:7], v[132:135], v[64:79]
	ds_read_b128 v[4:7], v12 offset:47200
	s_waitcnt lgkmcnt(0)
	v_mfma_f32_32x32x16_bf16 v[64:79], v[4:7], v[128:131], v[64:79]
	ds_read_b128 v[4:7], v12 offset:51712
	s_waitcnt lgkmcnt(0)
	v_mfma_f32_32x32x16_bf16 v[48:63], v[4:7], v[0:3], 0
	ds_read_b128 v[4:7], v12 offset:51744
	s_waitcnt lgkmcnt(0)
	v_mfma_f32_32x32x16_bf16 v[48:63], v[4:7], v[136:139], v[48:63]
	ds_read_b128 v[4:7], v12 offset:51776
	s_waitcnt lgkmcnt(0)
	v_mfma_f32_32x32x16_bf16 v[48:63], v[4:7], v[132:135], v[48:63]
	ds_read_b128 v[4:7], v12 offset:51808
	s_waitcnt lgkmcnt(0)
	v_mfma_f32_32x32x16_bf16 v[48:63], v[4:7], v[128:131], v[48:63]
	ds_read_b128 v[4:7], v12 offset:56320
	s_waitcnt lgkmcnt(0)
	v_mfma_f32_32x32x16_bf16 v[32:47], v[4:7], v[0:3], 0
	ds_read_b128 v[4:7], v12 offset:56352
	s_waitcnt lgkmcnt(0)
	v_mfma_f32_32x32x16_bf16 v[32:47], v[4:7], v[136:139], v[32:47]
	ds_read_b128 v[4:7], v12 offset:56384
	s_waitcnt lgkmcnt(0)
	v_mfma_f32_32x32x16_bf16 v[32:47], v[4:7], v[132:135], v[32:47]
	ds_read_b128 v[4:7], v12 offset:56416
	s_waitcnt lgkmcnt(0)
	v_mfma_f32_32x32x16_bf16 v[32:47], v[4:7], v[128:131], v[32:47]
	ds_read_b128 v[4:7], v12 offset:60928
	s_waitcnt lgkmcnt(0)
	v_mfma_f32_32x32x16_bf16 v[16:31], v[4:7], v[0:3], 0
	ds_read_b128 v[4:7], v12 offset:60960
	s_waitcnt lgkmcnt(0)
	v_mfma_f32_32x32x16_bf16 v[16:31], v[4:7], v[136:139], v[16:31]
	ds_read_b128 v[4:7], v12 offset:60992
	s_waitcnt lgkmcnt(0)
	v_mfma_f32_32x32x16_bf16 v[16:31], v[4:7], v[132:135], v[16:31]
	ds_read_b128 v[4:7], v12 offset:61024
	s_waitcnt lgkmcnt(0)
	v_mfma_f32_32x32x16_bf16 v[16:31], v[4:7], v[128:131], v[16:31]
	ds_read_b128 v[4:7], v169 offset:32256
	ds_read_b128 v[176:179], v169 offset:32288
	s_waitcnt lgkmcnt(1)
	v_mfma_f32_32x32x16_bf16 v[0:15], v[4:7], v[0:3], 0
	s_waitcnt lgkmcnt(0)
	v_mfma_f32_32x32x16_bf16 v[0:15], v[176:179], v[136:139], v[0:15]
	ds_read_b128 v[136:139], v169 offset:32320
	s_waitcnt lgkmcnt(0)
	v_mfma_f32_32x32x16_bf16 v[0:15], v[136:139], v[132:135], v[0:15]
	ds_read_b128 v[132:135], v169 offset:32352
	s_waitcnt lgkmcnt(0)
	v_mfma_f32_32x32x16_bf16 v[0:15], v[132:135], v[128:131], v[0:15]
	v_max3_f32 v128, v112, s96, v113
	v_max3_f32 v128, v128, v114, v115
	v_max3_f32 v128, v128, v116, v117
	v_max3_f32 v128, v128, v118, v119
	v_max3_f32 v128, v128, v120, v121
	v_max3_f32 v128, v128, v122, v123
	v_max3_f32 v128, v128, v124, v125
	v_max3_f32 v128, v128, v126, v127
	v_max3_f32 v128, v128, v96, v97
	v_max3_f32 v128, v128, v98, v99
	v_max3_f32 v128, v128, v100, v101
	v_max3_f32 v128, v128, v102, v103
	v_max3_f32 v128, v128, v104, v105
	v_max3_f32 v128, v128, v106, v107
	v_max3_f32 v128, v128, v108, v109
	v_max3_f32 v128, v128, v110, v111
	v_max3_f32 v128, v128, v80, v81
	v_max3_f32 v128, v128, v82, v83
	v_max3_f32 v128, v128, v84, v85
	v_max3_f32 v128, v128, v86, v87
	v_max3_f32 v128, v128, v88, v89
	v_max3_f32 v128, v128, v90, v91
	v_max3_f32 v128, v128, v92, v93
	v_max3_f32 v128, v128, v94, v95
	v_max3_f32 v128, v128, v64, v65
	v_max3_f32 v128, v128, v66, v67
	v_max3_f32 v128, v128, v68, v69
	v_max3_f32 v128, v128, v70, v71
	v_max3_f32 v128, v128, v72, v73
	v_max3_f32 v128, v128, v74, v75
	v_max3_f32 v128, v128, v76, v77
	v_max3_f32 v128, v128, v78, v79
	v_max3_f32 v128, v128, v48, v49
	v_max3_f32 v128, v128, v50, v51
	v_max3_f32 v128, v128, v52, v53
	v_max3_f32 v128, v128, v54, v55
	v_max3_f32 v128, v128, v56, v57
	v_max3_f32 v128, v128, v58, v59
	v_max3_f32 v128, v128, v60, v61
	v_max3_f32 v128, v128, v62, v63
	v_max3_f32 v128, v128, v32, v33
	v_max3_f32 v128, v128, v34, v35
	v_max3_f32 v128, v128, v36, v37
	v_max3_f32 v128, v128, v38, v39
	v_max3_f32 v128, v128, v40, v41
	v_max3_f32 v128, v128, v42, v43
	v_max3_f32 v128, v128, v44, v45
	v_max3_f32 v128, v128, v46, v47
	v_max3_f32 v128, v128, v16, v17
	v_max3_f32 v128, v128, v18, v19
	v_max3_f32 v128, v128, v20, v21
	v_max3_f32 v128, v128, v22, v23
	v_max3_f32 v128, v128, v24, v25
	v_max3_f32 v128, v128, v26, v27
	v_max3_f32 v128, v128, v28, v29
	v_max3_f32 v128, v128, v30, v31
	v_max3_f32 v128, v128, v0, v1
	v_max3_f32 v128, v128, v2, v3
	v_max3_f32 v128, v128, v4, v5
	v_max3_f32 v128, v128, v6, v7
	v_max3_f32 v128, v128, v8, v9
	v_max3_f32 v128, v128, v10, v11
	v_max3_f32 v128, v128, v12, v13
	v_max3_f32 v128, v128, v14, v15
	ds_bpermute_b32 v129, v170, v128
	s_waitcnt lgkmcnt(0)
	v_max_f32_e32 v129, v129, v129
	v_max_f32_e32 v162, v128, v129
	v_sub_f32_e32 v112, v112, v162
	v_exp_f32_e32 v163, v112
	v_sub_f32_e32 v113, v113, v162
	v_exp_f32_e32 v164, v113
	v_sub_f32_e32 v113, v114, v162
	v_exp_f32_e32 v165, v113
	v_sub_f32_e32 v113, v115, v162
	v_exp_f32_e32 v192, v113
	v_sub_f32_e32 v113, v116, v162
	v_add_f32_e32 v112, 0, v163
	v_exp_f32_e32 v193, v113
	v_sub_f32_e32 v113, v117, v162
	v_add_f32_e32 v112, v164, v112
	v_exp_f32_e32 v194, v113
	v_sub_f32_e32 v113, v118, v162
	v_add_f32_e32 v112, v165, v112
	v_exp_f32_e32 v195, v113
	v_sub_f32_e32 v113, v119, v162
	v_add_f32_e32 v112, v192, v112
	v_exp_f32_e32 v196, v113
	v_add_f32_e32 v112, v193, v112
	v_add_f32_e32 v112, v194, v112
	v_add_f32_e32 v112, v195, v112
	v_add_f32_e32 v113, v196, v112
	v_sub_f32_e32 v112, v120, v162
	v_exp_f32_e32 v112, v112
	v_sub_f32_e32 v96, v96, v162
	v_exp_f32_e32 v96, v96
	v_sub_f32_e32 v97, v97, v162
	v_add_f32_e32 v114, v112, v113
	v_sub_f32_e32 v113, v121, v162
	v_exp_f32_e32 v113, v113
	v_exp_f32_e32 v97, v97
	v_sub_f32_e32 v98, v98, v162
	v_exp_f32_e32 v98, v98
	v_add_f32_e32 v115, v113, v114
	v_sub_f32_e32 v114, v122, v162
	v_exp_f32_e32 v114, v114
	v_sub_f32_e32 v99, v99, v162
	v_exp_f32_e32 v99, v99
	v_sub_f32_e32 v100, v100, v162
	v_add_f32_e32 v116, v114, v115
	v_sub_f32_e32 v115, v123, v162
	v_exp_f32_e32 v115, v115
	v_exp_f32_e32 v100, v100
	v_sub_f32_e32 v101, v101, v162
	v_exp_f32_e32 v101, v101
	v_add_f32_e32 v117, v115, v116
	v_sub_f32_e32 v116, v124, v162
	v_exp_f32_e32 v116, v116
	v_sub_f32_e32 v102, v102, v162
	v_exp_f32_e32 v102, v102
	v_sub_f32_e32 v103, v103, v162
	v_add_f32_e32 v118, v116, v117
	v_sub_f32_e32 v117, v125, v162
	v_exp_f32_e32 v117, v117
	v_sub_f32_e32 v80, v80, v162
	v_exp_f32_e32 v80, v80
	v_sub_f32_e32 v81, v81, v162
	v_add_f32_e32 v119, v117, v118
	v_sub_f32_e32 v118, v126, v162
	v_exp_f32_e32 v118, v118
	v_exp_f32_e32 v81, v81
	v_sub_f32_e32 v82, v82, v162
	v_exp_f32_e32 v82, v82
	v_add_f32_e32 v120, v118, v119
	v_sub_f32_e32 v119, v127, v162
	v_exp_f32_e32 v119, v119
	v_sub_f32_e32 v83, v83, v162
	v_exp_f32_e32 v83, v83
	v_sub_f32_e32 v84, v84, v162
	v_add_f32_e32 v120, v119, v120
	v_add_f32_e32 v120, v96, v120
	v_add_f32_e32 v120, v97, v120
	v_add_f32_e32 v120, v98, v120
	v_add_f32_e32 v120, v99, v120
	v_add_f32_e32 v120, v100, v120
	v_add_f32_e32 v120, v101, v120
	v_add_f32_e32 v121, v102, v120
	v_exp_f32_e32 v120, v103
	v_sub_f32_e32 v103, v104, v162
	v_exp_f32_e32 v103, v103
	v_sub_f32_e32 v104, v105, v162
	v_exp_f32_e32 v104, v104
	v_sub_f32_e32 v105, v106, v162
	v_exp_f32_e32 v105, v105
	v_sub_f32_e32 v106, v107, v162
	v_add_f32_e32 v121, v120, v121
	v_exp_f32_e32 v106, v106
	v_sub_f32_e32 v107, v108, v162
	v_add_f32_e32 v121, v103, v121
	v_exp_f32_e32 v107, v107
	v_sub_f32_e32 v108, v109, v162
	v_add_f32_e32 v121, v104, v121
	v_exp_f32_e32 v108, v108
	v_sub_f32_e32 v109, v110, v162
	v_add_f32_e32 v121, v105, v121
	v_exp_f32_e32 v109, v109
	v_sub_f32_e32 v110, v111, v162
	v_add_f32_e32 v121, v106, v121
	v_exp_f32_e32 v110, v110
	v_add_f32_e32 v121, v107, v121
	v_add_f32_e32 v121, v108, v121
	v_add_f32_e32 v121, v109, v121
	v_add_f32_e32 v111, v110, v121
	v_add_f32_e32 v111, v80, v111
	v_exp_f32_e32 v84, v84
	v_sub_f32_e32 v85, v85, v162
	v_add_f32_e32 v111, v81, v111
	v_exp_f32_e32 v85, v85
	v_sub_f32_e32 v86, v86, v162
	v_add_f32_e32 v111, v82, v111
	v_exp_f32_e32 v86, v86
	v_add_f32_e32 v111, v83, v111
	v_add_f32_e32 v111, v84, v111
	v_add_f32_e32 v111, v85, v111
	v_sub_f32_e32 v87, v87, v162
	v_add_f32_e32 v121, v86, v111
	v_exp_f32_e32 v111, v87
	v_sub_f32_e32 v87, v88, v162
	v_exp_f32_e32 v87, v87
	v_sub_f32_e32 v88, v89, v162
	v_exp_f32_e32 v88, v88
	v_sub_f32_e32 v89, v90, v162
	v_exp_f32_e32 v89, v89
	v_sub_f32_e32 v90, v91, v162
	v_add_f32_e32 v121, v111, v121
	v_exp_f32_e32 v90, v90
	v_sub_f32_e32 v91, v92, v162
	v_add_f32_e32 v121, v87, v121
	v_exp_f32_e32 v91, v91
	v_sub_f32_e32 v92, v93, v162
	v_add_f32_e32 v121, v88, v121
	v_exp_f32_e32 v92, v92
	v_sub_f32_e32 v93, v94, v162
	v_add_f32_e32 v121, v89, v121
	v_exp_f32_e32 v93, v93
	v_sub_f32_e32 v94, v95, v162
	v_add_f32_e32 v121, v90, v121
	v_exp_f32_e32 v94, v94
	v_sub_f32_e32 v64, v64, v162
	v_add_f32_e32 v121, v91, v121
	v_exp_f32_e32 v64, v64
	v_sub_f32_e32 v65, v65, v162
	v_add_f32_e32 v121, v92, v121
	v_exp_f32_e32 v65, v65
	v_sub_f32_e32 v66, v66, v162
	v_add_f32_e32 v121, v93, v121
	v_exp_f32_e32 v66, v66
	v_sub_f32_e32 v67, v67, v162
	v_add_f32_e32 v95, v94, v121
	v_exp_f32_e32 v67, v67
	v_sub_f32_e32 v68, v68, v162
	v_add_f32_e32 v95, v64, v95
	v_exp_f32_e32 v68, v68
	v_sub_f32_e32 v69, v69, v162
	v_add_f32_e32 v95, v65, v95
	v_exp_f32_e32 v69, v69
	v_sub_f32_e32 v70, v70, v162
	v_add_f32_e32 v95, v66, v95
	v_exp_f32_e32 v70, v70
	v_add_f32_e32 v95, v67, v95
	v_add_f32_e32 v95, v68, v95
	v_add_f32_e32 v95, v69, v95
	v_sub_f32_e32 v71, v71, v162
	v_add_f32_e32 v121, v70, v95
	v_exp_f32_e32 v95, v71
	v_sub_f32_e32 v71, v72, v162
	v_exp_f32_e32 v71, v71
	v_sub_f32_e32 v72, v73, v162
	v_exp_f32_e32 v72, v72
	v_sub_f32_e32 v73, v74, v162
	v_exp_f32_e32 v73, v73
	v_sub_f32_e32 v74, v75, v162
	v_add_f32_e32 v121, v95, v121
	v_exp_f32_e32 v74, v74
	v_sub_f32_e32 v75, v76, v162
	v_add_f32_e32 v121, v71, v121
	v_exp_f32_e32 v75, v75
	v_sub_f32_e32 v76, v77, v162
	v_add_f32_e32 v121, v72, v121
	v_exp_f32_e32 v76, v76
	v_sub_f32_e32 v77, v78, v162
	v_add_f32_e32 v121, v73, v121
	v_exp_f32_e32 v77, v77
	v_sub_f32_e32 v78, v79, v162
	v_add_f32_e32 v121, v74, v121
	v_exp_f32_e32 v78, v78
	v_sub_f32_e32 v48, v48, v162
	v_add_f32_e32 v121, v75, v121
	v_exp_f32_e32 v48, v48
	v_sub_f32_e32 v49, v49, v162
	v_add_f32_e32 v121, v76, v121
	v_exp_f32_e32 v49, v49
	v_sub_f32_e32 v50, v50, v162
	v_add_f32_e32 v121, v77, v121
	v_exp_f32_e32 v50, v50
	v_sub_f32_e32 v51, v51, v162
	v_add_f32_e32 v79, v78, v121
	v_exp_f32_e32 v51, v51
	v_sub_f32_e32 v52, v52, v162
	v_add_f32_e32 v79, v48, v79
	v_exp_f32_e32 v52, v52
	v_sub_f32_e32 v53, v53, v162
	v_add_f32_e32 v79, v49, v79
	v_exp_f32_e32 v53, v53
	v_sub_f32_e32 v54, v54, v162
	v_add_f32_e32 v79, v50, v79
	v_exp_f32_e32 v54, v54
	v_add_f32_e32 v79, v51, v79
	v_add_f32_e32 v79, v52, v79
	v_add_f32_e32 v79, v53, v79
	v_sub_f32_e32 v55, v55, v162
	v_add_f32_e32 v121, v54, v79
	v_exp_f32_e32 v79, v55
	v_sub_f32_e32 v55, v56, v162
	v_exp_f32_e32 v55, v55
	v_sub_f32_e32 v56, v57, v162
	v_exp_f32_e32 v56, v56
	v_sub_f32_e32 v57, v58, v162
	v_exp_f32_e32 v57, v57
	v_sub_f32_e32 v58, v59, v162
	v_add_f32_e32 v121, v79, v121
	v_exp_f32_e32 v58, v58
	v_sub_f32_e32 v59, v60, v162
	v_add_f32_e32 v121, v55, v121
	v_exp_f32_e32 v59, v59
	v_sub_f32_e32 v60, v61, v162
	v_add_f32_e32 v121, v56, v121
	v_exp_f32_e32 v60, v60
	v_sub_f32_e32 v61, v62, v162
	v_add_f32_e32 v121, v57, v121
	v_exp_f32_e32 v61, v61
	v_sub_f32_e32 v63, v63, v162
	v_add_f32_e32 v121, v58, v121
	v_exp_f32_e32 v63, v63
	v_add_f32_e32 v121, v59, v121
	v_add_f32_e32 v121, v60, v121
	v_add_f32_e32 v62, v61, v121
	v_sub_f32_e32 v32, v32, v162
	v_add_f32_e32 v121, v63, v62
	v_exp_f32_e32 v62, v32
	v_sub_f32_e32 v33, v33, v162
	v_sub_f32_e32 v16, v16, v162
	v_sub_f32_e32 v17, v17, v162
	v_add_f32_e32 v32, v62, v121
	v_exp_f32_e32 v121, v33
	v_sub_f32_e32 v33, v34, v162
	v_exp_f32_e32 v122, v33
	v_sub_f32_e32 v33, v35, v162
	v_exp_f32_e32 v123, v33
	v_sub_f32_e32 v33, v36, v162
	v_exp_f32_e32 v36, v33
	v_sub_f32_e32 v33, v37, v162
	v_add_f32_e32 v32, v121, v32
	v_exp_f32_e32 v37, v33
	v_sub_f32_e32 v33, v38, v162
	v_add_f32_e32 v32, v122, v32
	v_exp_f32_e32 v38, v33
	v_sub_f32_e32 v33, v39, v162
	v_add_f32_e32 v32, v123, v32
	v_exp_f32_e32 v124, v33
	v_sub_f32_e32 v33, v40, v162
	v_add_f32_e32 v32, v36, v32
	v_exp_f32_e32 v39, v33
	v_sub_f32_e32 v33, v41, v162
	v_add_f32_e32 v32, v37, v32
	v_exp_f32_e32 v40, v33
	v_sub_f32_e32 v33, v42, v162
	v_add_f32_e32 v32, v38, v32
	v_exp_f32_e32 v41, v33
	v_sub_f32_e32 v33, v43, v162
	v_add_f32_e32 v32, v124, v32
	v_exp_f32_e32 v42, v33
	v_sub_f32_e32 v33, v44, v162
	v_add_f32_e32 v32, v39, v32
	v_exp_f32_e32 v43, v33
	v_sub_f32_e32 v33, v45, v162
	v_add_f32_e32 v32, v40, v32
	v_exp_f32_e32 v44, v33
	v_sub_f32_e32 v33, v46, v162
	v_add_f32_e32 v32, v41, v32
	v_exp_f32_e32 v45, v33
	v_sub_f32_e32 v33, v47, v162
	v_add_f32_e32 v32, v42, v32
	v_exp_f32_e32 v47, v33
	v_add_f32_e32 v32, v43, v32
	v_exp_f32_e32 v46, v16
	v_add_f32_e32 v32, v44, v32
	v_exp_f32_e32 v125, v17
	v_sub_f32_e32 v17, v18, v162
	v_add_f32_e32 v32, v45, v32
	v_exp_f32_e32 v126, v17
	v_sub_f32_e32 v17, v19, v162
	v_add_f32_e32 v32, v47, v32
	v_exp_f32_e32 v127, v17
	v_sub_f32_e32 v17, v20, v162
	v_add_f32_e32 v16, v46, v32
	v_exp_f32_e32 v128, v17
	v_sub_f32_e32 v17, v21, v162
	v_add_f32_e32 v16, v125, v16
	v_exp_f32_e32 v129, v17
	v_sub_f32_e32 v17, v22, v162
	v_add_f32_e32 v16, v126, v16
	v_exp_f32_e32 v130, v17
	v_sub_f32_e32 v17, v23, v162
	v_add_f32_e32 v16, v127, v16
	v_exp_f32_e32 v132, v17
	v_sub_f32_e32 v17, v24, v162
	v_add_f32_e32 v16, v128, v16
	v_exp_f32_e32 v131, v17
	v_sub_f32_e32 v17, v25, v162
	v_add_f32_e32 v16, v129, v16
	v_exp_f32_e32 v133, v17
	v_sub_f32_e32 v17, v26, v162
	v_add_f32_e32 v16, v130, v16
	v_exp_f32_e32 v134, v17
	v_sub_f32_e32 v17, v27, v162
	v_add_f32_e32 v16, v132, v16
	v_exp_f32_e32 v135, v17
	v_sub_f32_e32 v17, v28, v162
	v_add_f32_e32 v16, v131, v16
	v_exp_f32_e32 v136, v17
	v_sub_f32_e32 v17, v29, v162
	v_add_f32_e32 v16, v133, v16
	v_exp_f32_e32 v137, v17
	v_sub_f32_e32 v17, v30, v162
	v_add_f32_e32 v16, v134, v16
	v_exp_f32_e32 v138, v17
	v_sub_f32_e32 v17, v31, v162
	v_add_f32_e32 v16, v135, v16
	v_exp_f32_e32 v149, v17
	v_sub_f32_e32 v0, v0, v162
	v_add_f32_e32 v16, v136, v16
	v_exp_f32_e32 v139, v0
	v_sub_f32_e32 v1, v1, v162
	v_add_f32_e32 v16, v137, v16
	v_exp_f32_e32 v151, v1
	v_sub_f32_e32 v1, v2, v162
	v_add_f32_e32 v16, v138, v16
	v_exp_f32_e32 v176, v1
	v_sub_f32_e32 v1, v3, v162
	v_add_f32_e32 v16, v149, v16
	v_exp_f32_e32 v177, v1
	v_sub_f32_e32 v1, v4, v162
	v_add_f32_e32 v0, v139, v16
	v_exp_f32_e32 v178, v1
	v_sub_f32_e32 v1, v5, v162
	v_add_f32_e32 v0, v151, v0
	v_exp_f32_e32 v179, v1
	v_sub_f32_e32 v1, v6, v162
	v_add_f32_e32 v0, v176, v0
	v_exp_f32_e32 v180, v1
	v_sub_f32_e32 v1, v7, v162
	v_add_f32_e32 v0, v177, v0
	v_exp_f32_e32 v182, v1
	v_sub_f32_e32 v1, v8, v162
	v_add_f32_e32 v0, v178, v0
	v_exp_f32_e32 v181, v1
	v_sub_f32_e32 v1, v9, v162
	v_add_f32_e32 v0, v179, v0
	v_exp_f32_e32 v183, v1
	v_sub_f32_e32 v1, v10, v162
	v_add_f32_e32 v0, v180, v0
	v_exp_f32_e32 v184, v1
	v_sub_f32_e32 v1, v11, v162
	v_add_f32_e32 v0, v182, v0
	v_exp_f32_e32 v185, v1
	v_sub_f32_e32 v1, v12, v162
	v_add_f32_e32 v0, v181, v0
	v_exp_f32_e32 v186, v1
	v_sub_f32_e32 v1, v13, v162
	v_add_f32_e32 v0, v183, v0
	v_exp_f32_e32 v187, v1
	v_sub_f32_e32 v1, v14, v162
	v_add_f32_e32 v0, v184, v0
	v_exp_f32_e32 v189, v1
	v_sub_f32_e32 v1, v15, v162
	v_add_f32_e32 v0, v185, v0
	v_exp_f32_e32 v191, v1
	v_add_f32_e32 v0, v186, v0
	v_add_f32_e32 v0, v187, v0
	v_add_f32_e32 v0, v189, v0
	v_add_f32_e32 v188, v191, v0
	ds_read2_b64 v[0:3], v175 offset1:2
	ds_read2_b64 v[32:35], v175 offset0:4 offset1:6
	v_cvt_pk_bf16_f32 v16, v163, v164
	v_cvt_pk_bf16_f32 v17, v165, v192
	v_cvt_pk_bf16_f32 v18, v193, v194
	v_cvt_pk_bf16_f32 v19, v195, v196
	v_add_u32_e32 v162, 0x4000, v175
	ds_read2_b64 v[20:23], v162 offset0:32 offset1:34
	s_waitcnt lgkmcnt(2)
	v_mfma_f32_32x32x16_bf16 v[0:15], v[0:3], v[16:19], 0
	v_cvt_pk_bf16_f32 v112, v112, v113
	v_cvt_pk_bf16_f32 v113, v114, v115
	v_cvt_pk_bf16_f32 v114, v116, v117
	v_cvt_pk_bf16_f32 v115, v118, v119
	ds_bpermute_b32 v190, v170, v188
	s_waitcnt lgkmcnt(2)
	v_mfma_f32_32x32x16_bf16 v[0:15], v[32:35], v[112:115], v[0:15]
	ds_read2_b64 v[32:35], v162 offset0:36 offset1:38
	s_waitcnt lgkmcnt(2)
	v_mfma_f32_32x32x16_bf16 v[16:31], v[20:23], v[16:19], 0
	s_waitcnt lgkmcnt(0)
	v_mfma_f32_32x32x16_bf16 v[16:31], v[32:35], v[112:115], v[16:31]
	v_cvt_pk_bf16_f32 v32, v96, v97
	v_cvt_pk_bf16_f32 v33, v98, v99
	ds_read2_b64 v[96:99], v175 offset0:8 offset1:10
	v_cvt_pk_bf16_f32 v34, v100, v101
	v_cvt_pk_bf16_f32 v35, v102, v120
	s_waitcnt lgkmcnt(0)
	s_nop 0
	v_mfma_f32_32x32x16_bf16 v[0:15], v[96:99], v[32:35], v[0:15]
	ds_read2_b64 v[96:99], v162 offset0:40 offset1:42
	s_waitcnt lgkmcnt(0)
	v_mfma_f32_32x32x16_bf16 v[16:31], v[96:99], v[32:35], v[16:31]
	ds_read2_b64 v[96:99], v175 offset0:12 offset1:14
	v_cvt_pk_bf16_f32 v32, v103, v104
	v_cvt_pk_bf16_f32 v33, v105, v106
	v_cvt_pk_bf16_f32 v34, v107, v108
	v_cvt_pk_bf16_f32 v35, v109, v110
	s_waitcnt lgkmcnt(0)
	s_nop 0
	v_mfma_f32_32x32x16_bf16 v[0:15], v[96:99], v[32:35], v[0:15]
	ds_read2_b64 v[96:99], v162 offset0:44 offset1:46
	s_waitcnt lgkmcnt(0)
	v_mfma_f32_32x32x16_bf16 v[16:31], v[96:99], v[32:35], v[16:31]
	v_cvt_pk_bf16_f32 v32, v80, v81
	v_cvt_pk_bf16_f32 v33, v82, v83
	ds_read2_b64 v[80:83], v175 offset0:16 offset1:18
	v_cvt_pk_bf16_f32 v34, v84, v85
	v_cvt_pk_bf16_f32 v35, v86, v111
	s_waitcnt lgkmcnt(0)
	s_nop 0
	v_mfma_f32_32x32x16_bf16 v[0:15], v[80:83], v[32:35], v[0:15]
	ds_read2_b64 v[80:83], v162 offset0:48 offset1:50
	s_waitcnt lgkmcnt(0)
	v_mfma_f32_32x32x16_bf16 v[16:31], v[80:83], v[32:35], v[16:31]
	ds_read2_b64 v[80:83], v175 offset0:20 offset1:22
	v_cvt_pk_bf16_f32 v32, v87, v88
	v_cvt_pk_bf16_f32 v33, v89, v90
	v_cvt_pk_bf16_f32 v34, v91, v92
	v_cvt_pk_bf16_f32 v35, v93, v94
	s_waitcnt lgkmcnt(0)
	s_nop 0
	v_mfma_f32_32x32x16_bf16 v[0:15], v[80:83], v[32:35], v[0:15]
	ds_read2_b64 v[80:83], v162 offset0:52 offset1:54
	s_waitcnt lgkmcnt(0)
	v_mfma_f32_32x32x16_bf16 v[16:31], v[80:83], v[32:35], v[16:31]
	v_cvt_pk_bf16_f32 v32, v64, v65
	v_cvt_pk_bf16_f32 v33, v66, v67
	ds_read2_b64 v[64:67], v175 offset0:24 offset1:26
	v_cvt_pk_bf16_f32 v34, v68, v69
	v_cvt_pk_bf16_f32 v35, v70, v95
	s_waitcnt lgkmcnt(0)
	s_nop 0
	v_mfma_f32_32x32x16_bf16 v[0:15], v[64:67], v[32:35], v[0:15]
	ds_read2_b64 v[64:67], v162 offset0:56 offset1:58
	s_waitcnt lgkmcnt(0)
	v_mfma_f32_32x32x16_bf16 v[16:31], v[64:67], v[32:35], v[16:31]
	ds_read2_b64 v[64:67], v175 offset0:28 offset1:30
	v_cvt_pk_bf16_f32 v32, v71, v72
	v_cvt_pk_bf16_f32 v33, v73, v74
	v_cvt_pk_bf16_f32 v34, v75, v76
	v_cvt_pk_bf16_f32 v35, v77, v78
	s_waitcnt lgkmcnt(0)
	s_nop 0
	v_mfma_f32_32x32x16_bf16 v[0:15], v[64:67], v[32:35], v[0:15]
	ds_read2_b64 v[64:67], v162 offset0:60 offset1:62
	s_waitcnt lgkmcnt(0)
	v_mfma_f32_32x32x16_bf16 v[16:31], v[64:67], v[32:35], v[16:31]
	v_cvt_pk_bf16_f32 v32, v48, v49
	v_cvt_pk_bf16_f32 v33, v50, v51
	ds_read2_b64 v[48:51], v175 offset0:32 offset1:34
	v_cvt_pk_bf16_f32 v34, v52, v53
	v_cvt_pk_bf16_f32 v35, v54, v79
	s_waitcnt lgkmcnt(0)
	s_nop 0
	v_mfma_f32_32x32x16_bf16 v[0:15], v[48:51], v[32:35], v[0:15]
	ds_read2_b64 v[48:51], v162 offset0:64 offset1:66
	s_waitcnt lgkmcnt(0)
	v_mfma_f32_32x32x16_bf16 v[16:31], v[48:51], v[32:35], v[16:31]
	ds_read2_b64 v[48:51], v175 offset0:36 offset1:38
	v_cvt_pk_bf16_f32 v32, v55, v56
	v_cvt_pk_bf16_f32 v33, v57, v58
	v_cvt_pk_bf16_f32 v34, v59, v60
	v_cvt_pk_bf16_f32 v35, v61, v63
	s_waitcnt lgkmcnt(0)
	s_nop 0
	v_mfma_f32_32x32x16_bf16 v[0:15], v[48:51], v[32:35], v[0:15]
	ds_read2_b64 v[48:51], v162 offset0:68 offset1:70
	s_waitcnt lgkmcnt(0)
	v_mfma_f32_32x32x16_bf16 v[16:31], v[48:51], v[32:35], v[16:31]
	ds_read2_b64 v[48:51], v175 offset0:40 offset1:42
	v_cvt_pk_bf16_f32 v32, v62, v121
	v_cvt_pk_bf16_f32 v33, v122, v123
	v_cvt_pk_bf16_f32 v34, v36, v37
	v_cvt_pk_bf16_f32 v35, v38, v124
	s_waitcnt lgkmcnt(0)
	s_nop 0
	v_mfma_f32_32x32x16_bf16 v[0:15], v[48:51], v[32:35], v[0:15]
	ds_read2_b64 v[48:51], v162 offset0:72 offset1:74
	s_waitcnt lgkmcnt(0)
	v_mfma_f32_32x32x16_bf16 v[16:31], v[48:51], v[32:35], v[16:31]
	v_cvt_pk_bf16_f32 v32, v39, v40
	ds_read2_b64 v[36:39], v175 offset0:44 offset1:46
	v_cvt_pk_bf16_f32 v33, v41, v42
	v_cvt_pk_bf16_f32 v34, v43, v44
	v_cvt_pk_bf16_f32 v35, v45, v47
	s_waitcnt lgkmcnt(0)
	s_nop 0
	v_mfma_f32_32x32x16_bf16 v[0:15], v[36:39], v[32:35], v[0:15]
	ds_read2_b64 v[36:39], v162 offset0:76 offset1:78
	s_waitcnt lgkmcnt(0)
	v_mfma_f32_32x32x16_bf16 v[16:31], v[36:39], v[32:35], v[16:31]
	ds_read2_b64 v[36:39], v175 offset0:48 offset1:50
	v_cvt_pk_bf16_f32 v32, v46, v125
	v_cvt_pk_bf16_f32 v33, v126, v127
	v_cvt_pk_bf16_f32 v34, v128, v129
	v_cvt_pk_bf16_f32 v35, v130, v132
	s_waitcnt lgkmcnt(0)
	s_nop 0
	v_mfma_f32_32x32x16_bf16 v[0:15], v[36:39], v[32:35], v[0:15]
	ds_read2_b64 v[36:39], v162 offset0:80 offset1:82
	s_waitcnt lgkmcnt(0)
	v_mfma_f32_32x32x16_bf16 v[16:31], v[36:39], v[32:35], v[16:31]
	ds_read2_b64 v[36:39], v175 offset0:52 offset1:54
	v_cvt_pk_bf16_f32 v32, v131, v133
	v_cvt_pk_bf16_f32 v33, v134, v135
	v_cvt_pk_bf16_f32 v34, v136, v137
	v_cvt_pk_bf16_f32 v35, v138, v149
	s_waitcnt lgkmcnt(0)
	s_nop 0
	v_mfma_f32_32x32x16_bf16 v[0:15], v[36:39], v[32:35], v[0:15]
	ds_read2_b64 v[36:39], v162 offset0:84 offset1:86
	s_waitcnt lgkmcnt(0)
	v_mfma_f32_32x32x16_bf16 v[16:31], v[36:39], v[32:35], v[16:31]
	ds_read2_b64 v[36:39], v175 offset0:56 offset1:58
	v_cvt_pk_bf16_f32 v32, v139, v151
	v_cvt_pk_bf16_f32 v33, v176, v177
	v_cvt_pk_bf16_f32 v34, v178, v179
	v_cvt_pk_bf16_f32 v35, v180, v182
	v_mov_b32_e32 v151, v161
	s_waitcnt lgkmcnt(0)
	v_mfma_f32_32x32x16_bf16 v[0:15], v[36:39], v[32:35], v[0:15]
	ds_read2_b64 v[36:39], v162 offset0:88 offset1:90
	s_waitcnt lgkmcnt(0)
	v_mfma_f32_32x32x16_bf16 v[16:31], v[36:39], v[32:35], v[16:31]
	ds_read2_b64 v[36:39], v175 offset0:60 offset1:62
	v_cvt_pk_bf16_f32 v32, v181, v183
	v_cvt_pk_bf16_f32 v33, v184, v185
	v_cvt_pk_bf16_f32 v34, v186, v187
	v_cvt_pk_bf16_f32 v35, v189, v191
	s_waitcnt lgkmcnt(0)
	s_nop 0
	v_mfma_f32_32x32x16_bf16 v[0:15], v[36:39], v[32:35], v[0:15]
	ds_read2_b64 v[36:39], v162 offset0:92 offset1:94
	s_waitcnt lgkmcnt(0)
	v_mfma_f32_32x32x16_bf16 v[16:31], v[36:39], v[32:35], v[16:31]
	v_add_f32_e32 v32, v188, v190
	v_div_scale_f32 v33, s[12:13], v32, v32, 1.0
	v_rcp_f32_e32 v34, v33
	s_nop 0
	v_fma_f32 v35, -v33, v34, 1.0
	v_fmac_f32_e32 v34, v35, v34
	v_div_scale_f32 v35, vcc, 1.0, v32, 1.0
	v_mul_f32_e32 v36, v35, v34
	v_fma_f32 v37, -v33, v36, v35
	v_fmac_f32_e32 v36, v37, v34
	v_fma_f32 v33, -v33, v36, v35
	v_div_fmas_f32 v33, v33, v34, v36
	v_div_fixup_f32 v32, v33, v32, 1.0
	v_lshl_add_u64 v[34:35], s[20:21], 0, v[152:153]
	v_lshl_add_u64 v[34:35], v[34:35], 0, s[4:5]
	v_pk_mul_f32 v[0:1], v[0:1], v[32:33] op_sel_hi:[1,0]
	v_pk_mul_f32 v[2:3], v[2:3], v[32:33] op_sel_hi:[1,0]
	v_lshl_add_u64 v[34:35], v[34:35], 0, v[150:151]
	v_cvt_pk_bf16_f32 v0, v0, v1
	v_cvt_pk_bf16_f32 v1, v2, v3
	global_store_dwordx2 v[34:35], v[0:1], off offset:1536
	v_pk_mul_f32 v[0:1], v[4:5], v[32:33] op_sel_hi:[1,0]
	v_pk_mul_f32 v[2:3], v[6:7], v[32:33] op_sel_hi:[1,0]
	v_cvt_pk_bf16_f32 v0, v0, v1
	v_cvt_pk_bf16_f32 v1, v2, v3
	global_store_dwordx2 v[34:35], v[0:1], off offset:1552
	v_pk_mul_f32 v[0:1], v[8:9], v[32:33] op_sel_hi:[1,0]
	v_pk_mul_f32 v[2:3], v[10:11], v[32:33] op_sel_hi:[1,0]
	v_cvt_pk_bf16_f32 v0, v0, v1
	v_cvt_pk_bf16_f32 v1, v2, v3
	global_store_dwordx2 v[34:35], v[0:1], off offset:1568
	v_pk_mul_f32 v[0:1], v[12:13], v[32:33] op_sel_hi:[1,0]
	v_pk_mul_f32 v[2:3], v[14:15], v[32:33] op_sel_hi:[1,0]
	v_cvt_pk_bf16_f32 v0, v0, v1
	v_cvt_pk_bf16_f32 v1, v2, v3
	global_store_dwordx2 v[34:35], v[0:1], off offset:1584
	v_pk_mul_f32 v[0:1], v[16:17], v[32:33] op_sel_hi:[1,0]
	v_pk_mul_f32 v[2:3], v[18:19], v[32:33] op_sel_hi:[1,0]
	v_cvt_pk_bf16_f32 v0, v0, v1
	v_cvt_pk_bf16_f32 v1, v2, v3
	global_store_dwordx2 v[34:35], v[0:1], off offset:1600
	v_pk_mul_f32 v[0:1], v[20:21], v[32:33] op_sel_hi:[1,0]
	v_pk_mul_f32 v[2:3], v[22:23], v[32:33] op_sel_hi:[1,0]
	v_cvt_pk_bf16_f32 v0, v0, v1
	v_cvt_pk_bf16_f32 v1, v2, v3
	global_store_dwordx2 v[34:35], v[0:1], off offset:1616
	v_pk_mul_f32 v[0:1], v[24:25], v[32:33] op_sel_hi:[1,0]
	v_pk_mul_f32 v[2:3], v[26:27], v[32:33] op_sel_hi:[1,0]
	v_cvt_pk_bf16_f32 v0, v0, v1
	v_cvt_pk_bf16_f32 v1, v2, v3
	global_store_dwordx2 v[34:35], v[0:1], off offset:1632
	v_pk_mul_f32 v[0:1], v[28:29], v[32:33] op_sel_hi:[1,0]
	v_pk_mul_f32 v[2:3], v[30:31], v[32:33] op_sel_hi:[1,0]
	v_cvt_pk_bf16_f32 v0, v0, v1
	v_cvt_pk_bf16_f32 v1, v2, v3
	global_store_dwordx2 v[34:35], v[0:1], off offset:1648
	s_barrier
	s_cbranch_scc1 .LBB0_176

.LBB0_230:
	s_or_b64 exec, exec, s[6:7]
	v_mov_b32_e32 v0, s97
	s_waitcnt lgkmcnt(0)
	s_barrier
	ds_read_b32 v0, v0
	s_movk_i32 s4, 0xff
	s_mov_b64 s[6:7], -1
	s_waitcnt lgkmcnt(0)
	s_barrier
	v_cmp_lt_u32_e32 vcc, s4, v0
	v_readfirstlane_b32 s8, v0
	s_cbranch_vccnz .LBB0_225
	s_lshr_b32 s6, s8, 6
	s_lshl_b32 s4, s6, 20
	s_add_u32 s7, s12, s4
	s_addc_u32 s9, s13, 0
	s_lshl_b32 s4, s8, 3
	s_and_b32 s4, s4, 0x180
	s_add_u32 s10, s7, s4
	s_addc_u32 s11, s9, 0
	v_lshl_add_u64 v[4:5], s[10:11], 0, v[160:161]
	v_lshl_add_u64 v[6:7], v[4:5], 0, v[140:141]
	global_load_dwordx4 v[44:47], v[6:7], off offset:512
	v_lshl_add_u64 v[8:9], v[4:5], 0, v[142:143]
	v_lshl_add_u64 v[10:11], v[4:5], 0, v[144:145]
	v_lshl_add_u64 v[4:5], v[4:5], 0, v[146:147]
	s_lshl_b32 s7, s8, 8
	s_lshl_b32 s6, s6, 12
	s_and_b32 s7, s7, 0xf00
	s_or_b32 s6, s6, s7
	v_mov_b32_e32 v149, v161
	v_add_u32_e32 v56, v170, v169
	global_load_dwordx4 v[16:19], v[8:9], off offset:512
	global_load_dwordx4 v[20:23], v[10:11], off offset:512
	global_load_dwordx4 v[24:27], v[4:5], off offset:512
	global_load_dwordx4 v[28:31], v[6:7], off
	global_load_dwordx4 v[32:35], v[8:9], off
	global_load_dwordx4 v[36:39], v[10:11], off
	global_load_dwordx4 v[40:43], v[4:5], off
	v_add_u32_e32 v6, v158, v167
	v_add_u32_e32 v0, s6, v159
	v_ashrrev_i32_e32 v1, 31, v0
	v_lshlrev_b64 v[152:153], 11, v[0:1]
	v_lshl_add_u64 v[0:1], s[64:65], 0, v[152:153]
	v_lshl_add_u64 v[0:1], v[0:1], 0, s[4:5]
	v_lshl_add_u64 v[0:1], v[0:1], 0, v[148:149]
	global_load_dwordx4 v[48:51], v[0:1], off offset:1536
	global_load_dwordx4 v[136:139], v[0:1], off offset:1568
	global_load_dwordx4 v[132:135], v[0:1], off offset:1600
	global_load_dwordx4 v[128:131], v[0:1], off offset:1632
	s_waitcnt vmcnt(11)
	ds_write_b16 v154, v44
	ds_write_b16_d16_hi v154, v44 offset:520
	ds_write_b16 v154, v45 offset:1040
	ds_write_b16_d16_hi v154, v45 offset:1560
	ds_write_b16 v154, v46 offset:2080
	ds_write_b16_d16_hi v154, v46 offset:2600
	ds_write_b16 v154, v47 offset:3120
	ds_write_b16_d16_hi v154, v47 offset:3640
	s_waitcnt vmcnt(10)
	ds_write_b16 v155, v16
	ds_write_b16_d16_hi v155, v16 offset:520
	ds_write_b16 v155, v17 offset:1040
	ds_write_b16_d16_hi v155, v17 offset:1560
	ds_write_b16 v155, v18 offset:2080
	ds_write_b16_d16_hi v155, v18 offset:2600
	ds_write_b16 v155, v19 offset:3120
	ds_write_b16_d16_hi v155, v19 offset:3640
	s_waitcnt vmcnt(9)
	ds_write_b16 v156, v20
	ds_write_b16_d16_hi v156, v20 offset:520
	ds_write_b16 v156, v21 offset:1040
	ds_write_b16_d16_hi v156, v21 offset:1560
	ds_write_b16 v156, v22 offset:2080
	ds_write_b16_d16_hi v156, v22 offset:2600
	ds_write_b16 v156, v23 offset:3120
	ds_write_b16_d16_hi v156, v23 offset:3640
	s_waitcnt vmcnt(8)
	ds_write_b16 v157, v24
	ds_write_b16_d16_hi v157, v24 offset:520
	ds_write_b16 v157, v25 offset:1040
	ds_write_b16_d16_hi v157, v25 offset:1560
	ds_write_b16 v157, v26 offset:2080
	ds_write_b16_d16_hi v157, v26 offset:2600
	ds_write_b16 v157, v27 offset:3120
	ds_write_b16_d16_hi v157, v27 offset:3640
	s_waitcnt vmcnt(7)
	ds_write_b128 v6, v[28:31] offset:33280
	s_waitcnt vmcnt(6)
	ds_write_b128 v174, v[32:35] offset:33280
	s_waitcnt vmcnt(5)
	ds_write_b128 v175, v[36:39] offset:33280
	s_waitcnt vmcnt(4)
	ds_write_b128 v176, v[40:43] offset:33280
	s_waitcnt lgkmcnt(0)
	s_barrier
	ds_read_b128 v[0:3], v56 offset:33280
	ds_read_b128 v[4:7], v56 offset:33312
	s_waitcnt vmcnt(3) lgkmcnt(1)
	v_mfma_f32_32x32x16_bf16 v[112:127], v[0:3], v[48:51], 0
	ds_read_b128 v[0:3], v56 offset:33344
	ds_read_b128 v[32:35], v56 offset:56352
	ds_read_b128 v[52:55], v56 offset:60960
	s_waitcnt vmcnt(2) lgkmcnt(3)
	v_mfma_f32_32x32x16_bf16 v[112:127], v[4:7], v[136:139], v[112:127]
	s_waitcnt vmcnt(1) lgkmcnt(2)
	v_mfma_f32_32x32x16_bf16 v[112:127], v[0:3], v[132:135], v[112:127]
	ds_read_b128 v[0:3], v56 offset:33376
	s_waitcnt vmcnt(0) lgkmcnt(0)
	v_mfma_f32_32x32x16_bf16 v[112:127], v[0:3], v[128:131], v[112:127]
	ds_read_b128 v[0:3], v56 offset:37888
	s_waitcnt lgkmcnt(0)
	v_mfma_f32_32x32x16_bf16 v[96:111], v[0:3], v[48:51], 0
	ds_read_b128 v[0:3], v56 offset:37920
	s_waitcnt lgkmcnt(0)
	v_mfma_f32_32x32x16_bf16 v[96:111], v[0:3], v[136:139], v[96:111]
	ds_read_b128 v[0:3], v56 offset:37952
	s_waitcnt lgkmcnt(0)
	v_mfma_f32_32x32x16_bf16 v[96:111], v[0:3], v[132:135], v[96:111]
	ds_read_b128 v[0:3], v56 offset:37984
	s_waitcnt lgkmcnt(0)
	v_mfma_f32_32x32x16_bf16 v[96:111], v[0:3], v[128:131], v[96:111]
	ds_read_b128 v[0:3], v56 offset:42496
	s_waitcnt lgkmcnt(0)
	v_mfma_f32_32x32x16_bf16 v[80:95], v[0:3], v[48:51], 0
	ds_read_b128 v[0:3], v56 offset:42528
	s_waitcnt lgkmcnt(0)
	v_mfma_f32_32x32x16_bf16 v[80:95], v[0:3], v[136:139], v[80:95]
	ds_read_b128 v[0:3], v56 offset:42560
	s_waitcnt lgkmcnt(0)
	v_mfma_f32_32x32x16_bf16 v[80:95], v[0:3], v[132:135], v[80:95]
	ds_read_b128 v[0:3], v56 offset:42592
	s_waitcnt lgkmcnt(0)
	v_mfma_f32_32x32x16_bf16 v[80:95], v[0:3], v[128:131], v[80:95]
	ds_read_b128 v[0:3], v56 offset:47104
	s_waitcnt lgkmcnt(0)
	v_mfma_f32_32x32x16_bf16 v[64:79], v[0:3], v[48:51], 0
	ds_read_b128 v[0:3], v56 offset:47136
	s_waitcnt lgkmcnt(0)
	v_mfma_f32_32x32x16_bf16 v[64:79], v[0:3], v[136:139], v[64:79]
	ds_read_b128 v[0:3], v56 offset:47168
	s_waitcnt lgkmcnt(0)
	v_mfma_f32_32x32x16_bf16 v[64:79], v[0:3], v[132:135], v[64:79]
	ds_read_b128 v[0:3], v56 offset:47200
	s_waitcnt lgkmcnt(0)
	v_mfma_f32_32x32x16_bf16 v[64:79], v[0:3], v[128:131], v[64:79]
	ds_read_b128 v[0:3], v56 offset:51712
	s_waitcnt lgkmcnt(0)
	v_mfma_f32_32x32x16_bf16 v[16:31], v[0:3], v[48:51], 0
	ds_read_b128 v[0:3], v56 offset:51744
	s_waitcnt lgkmcnt(0)
	v_mfma_f32_32x32x16_bf16 v[16:31], v[0:3], v[136:139], v[16:31]
	ds_read_b128 v[0:3], v56 offset:51776
	s_waitcnt lgkmcnt(0)
	v_mfma_f32_32x32x16_bf16 v[16:31], v[0:3], v[132:135], v[16:31]
	ds_read_b128 v[0:3], v56 offset:51808
	s_waitcnt lgkmcnt(0)
	v_mfma_f32_32x32x16_bf16 v[16:31], v[0:3], v[128:131], v[16:31]
	ds_read_b128 v[0:3], v56 offset:56320
	s_waitcnt lgkmcnt(0)
	v_mfma_f32_32x32x16_bf16 v[0:15], v[0:3], v[48:51], 0
	v_mfma_f32_32x32x16_bf16 v[0:15], v[32:35], v[136:139], v[0:15]
	ds_read_b128 v[32:35], v56 offset:56384
	s_waitcnt lgkmcnt(0)
	v_mfma_f32_32x32x16_bf16 v[0:15], v[32:35], v[132:135], v[0:15]
	ds_read_b128 v[32:35], v56 offset:56416
	s_waitcnt lgkmcnt(0)
	v_mfma_f32_32x32x16_bf16 v[0:15], v[32:35], v[128:131], v[0:15]
	ds_read_b128 v[32:35], v56 offset:60928
	s_waitcnt lgkmcnt(0)
	v_mfma_f32_32x32x16_bf16 v[32:47], v[32:35], v[48:51], 0
	v_mfma_f32_32x32x16_bf16 v[32:47], v[52:55], v[136:139], v[32:47]
	ds_read_b128 v[52:55], v56 offset:60992
	s_waitcnt lgkmcnt(0)
	v_mfma_f32_32x32x16_bf16 v[32:47], v[52:55], v[132:135], v[32:47]
	ds_read_b128 v[52:55], v56 offset:61024
	s_waitcnt lgkmcnt(0)
	v_mfma_f32_32x32x16_bf16 v[32:47], v[52:55], v[128:131], v[32:47]
	ds_read_b128 v[52:55], v171 offset:32256
	ds_read_b128 v[178:181], v171 offset:32288
	s_waitcnt lgkmcnt(1)
	v_mfma_f32_32x32x16_bf16 v[48:63], v[52:55], v[48:51], 0
	s_waitcnt lgkmcnt(0)
	v_mfma_f32_32x32x16_bf16 v[48:63], v[178:181], v[136:139], v[48:63]
	ds_read_b128 v[136:139], v171 offset:32320
	s_waitcnt lgkmcnt(0)
	v_mfma_f32_32x32x16_bf16 v[48:63], v[136:139], v[132:135], v[48:63]
	ds_read_b128 v[132:135], v171 offset:32352
	s_waitcnt lgkmcnt(0)
	v_mfma_f32_32x32x16_bf16 v[48:63], v[132:135], v[128:131], v[48:63]
	v_max3_f32 v128, v112, s96, v113
	v_max3_f32 v128, v128, v114, v115
	v_max3_f32 v128, v128, v116, v117
	v_max3_f32 v128, v128, v118, v119
	v_max3_f32 v128, v128, v120, v121
	v_max3_f32 v128, v128, v122, v123
	v_max3_f32 v128, v128, v124, v125
	v_max3_f32 v128, v128, v126, v127
	v_max3_f32 v128, v128, v96, v97
	v_max3_f32 v128, v128, v98, v99
	v_max3_f32 v128, v128, v100, v101
	v_max3_f32 v128, v128, v102, v103
	v_max3_f32 v128, v128, v104, v105
	v_max3_f32 v128, v128, v106, v107
	v_max3_f32 v128, v128, v108, v109
	v_max3_f32 v128, v128, v110, v111
	v_max3_f32 v128, v128, v80, v81
	v_max3_f32 v128, v128, v82, v83
	v_max3_f32 v128, v128, v84, v85
	v_max3_f32 v128, v128, v86, v87
	v_max3_f32 v128, v128, v88, v89
	v_max3_f32 v128, v128, v90, v91
	v_max3_f32 v128, v128, v92, v93
	v_max3_f32 v128, v128, v94, v95
	v_max3_f32 v128, v128, v64, v65
	v_max3_f32 v128, v128, v66, v67
	v_max3_f32 v128, v128, v68, v69
	v_max3_f32 v128, v128, v70, v71
	v_max3_f32 v128, v128, v72, v73
	v_max3_f32 v128, v128, v74, v75
	v_max3_f32 v128, v128, v76, v77
	v_max3_f32 v128, v128, v78, v79
	v_max3_f32 v128, v128, v16, v17
	v_max3_f32 v128, v128, v18, v19
	v_max3_f32 v128, v128, v20, v21
	v_max3_f32 v128, v128, v22, v23
	v_max3_f32 v128, v128, v24, v25
	v_max3_f32 v128, v128, v26, v27
	v_max3_f32 v128, v128, v28, v29
	v_max3_f32 v128, v128, v30, v31
	v_max3_f32 v128, v128, v0, v1
	v_max3_f32 v128, v128, v2, v3
	v_max3_f32 v128, v128, v4, v5
	v_max3_f32 v128, v128, v6, v7
	v_max3_f32 v128, v128, v8, v9
	v_max3_f32 v128, v128, v10, v11
	v_max3_f32 v128, v128, v12, v13
	v_max3_f32 v128, v128, v14, v15
	v_max3_f32 v128, v128, v32, v33
	v_max3_f32 v128, v128, v34, v35
	v_max3_f32 v128, v128, v36, v37
	v_max3_f32 v128, v128, v38, v39
	v_max3_f32 v128, v128, v40, v41
	v_max3_f32 v128, v128, v42, v43
	v_max3_f32 v128, v128, v44, v45
	v_max3_f32 v128, v128, v46, v47
	v_max3_f32 v128, v128, v48, v49
	v_max3_f32 v128, v128, v50, v51
	v_max3_f32 v128, v128, v52, v53
	v_max3_f32 v128, v128, v54, v55
	v_max3_f32 v128, v128, v56, v57
	v_max3_f32 v128, v128, v58, v59
	v_max3_f32 v128, v128, v60, v61
	v_max3_f32 v128, v128, v62, v63
	ds_bpermute_b32 v129, v173, v128
	s_waitcnt lgkmcnt(0)
	v_max_f32_e32 v129, v129, v129
	v_max_f32_e32 v204, v128, v129
	v_sub_f32_e32 v112, v112, v204
	v_exp_f32_e32 v203, v112
	v_sub_f32_e32 v113, v113, v204
	v_exp_f32_e32 v205, v113
	v_sub_f32_e32 v113, v114, v204
	v_exp_f32_e32 v206, v113
	v_sub_f32_e32 v113, v115, v204
	v_exp_f32_e32 v207, v113
	v_sub_f32_e32 v113, v116, v204
	v_add_f32_e32 v112, 0, v203
	v_exp_f32_e32 v208, v113
	v_sub_f32_e32 v113, v117, v204
	v_add_f32_e32 v112, v205, v112
	v_exp_f32_e32 v209, v113
	v_sub_f32_e32 v113, v118, v204
	v_add_f32_e32 v112, v206, v112
	v_exp_f32_e32 v210, v113
	v_sub_f32_e32 v113, v119, v204
	v_add_f32_e32 v112, v207, v112
	v_exp_f32_e32 v211, v113
	v_add_f32_e32 v112, v208, v112
	v_add_f32_e32 v112, v209, v112
	v_add_f32_e32 v112, v210, v112
	v_add_f32_e32 v113, v211, v112
	v_sub_f32_e32 v112, v120, v204
	v_exp_f32_e32 v112, v112
	v_sub_f32_e32 v120, v127, v204
	v_exp_f32_e32 v120, v120
	v_sub_f32_e32 v96, v96, v204
	v_add_f32_e32 v114, v112, v113
	v_sub_f32_e32 v113, v121, v204
	v_exp_f32_e32 v113, v113
	v_sub_f32_e32 v97, v97, v204
	v_sub_f32_e32 v80, v80, v204
	v_exp_f32_e32 v80, v80
	v_add_f32_e32 v115, v113, v114
	v_sub_f32_e32 v114, v122, v204
	v_exp_f32_e32 v114, v114
	v_sub_f32_e32 v81, v81, v204
	v_exp_f32_e32 v81, v81
	v_sub_f32_e32 v82, v82, v204
	v_add_f32_e32 v116, v114, v115
	v_sub_f32_e32 v115, v123, v204
	v_exp_f32_e32 v115, v115
	v_exp_f32_e32 v195, v82
	v_sub_f32_e32 v83, v83, v204
	v_exp_f32_e32 v197, v83
	v_add_f32_e32 v117, v115, v116
	v_sub_f32_e32 v116, v124, v204
	v_exp_f32_e32 v116, v116
	v_sub_f32_e32 v83, v84, v204
	v_exp_f32_e32 v199, v83
	v_sub_f32_e32 v83, v85, v204
	v_add_f32_e32 v118, v116, v117
	v_sub_f32_e32 v117, v125, v204
	v_exp_f32_e32 v117, v117
	v_exp_f32_e32 v200, v83
	v_sub_f32_e32 v83, v86, v204
	v_exp_f32_e32 v201, v83
	v_add_f32_e32 v119, v117, v118
	v_sub_f32_e32 v118, v126, v204
	v_exp_f32_e32 v118, v118
	v_sub_f32_e32 v83, v87, v204
	v_exp_f32_e32 v202, v83
	v_sub_f32_e32 v83, v88, v204
	v_add_f32_e32 v119, v118, v119
	v_add_f32_e32 v121, v120, v119
	v_exp_f32_e32 v119, v96
	v_exp_f32_e32 v185, v83
	v_sub_f32_e32 v83, v89, v204
	v_exp_f32_e32 v187, v83
	v_add_f32_e32 v96, v119, v121
	v_exp_f32_e32 v121, v97
	v_sub_f32_e32 v97, v98, v204
	v_exp_f32_e32 v122, v97
	v_sub_f32_e32 v97, v99, v204
	v_exp_f32_e32 v123, v97
	v_sub_f32_e32 v97, v100, v204
	v_exp_f32_e32 v124, v97
	v_sub_f32_e32 v97, v101, v204
	v_add_f32_e32 v96, v121, v96
	v_exp_f32_e32 v125, v97
	v_sub_f32_e32 v97, v102, v204
	v_add_f32_e32 v96, v122, v96
	v_exp_f32_e32 v126, v97
	v_sub_f32_e32 v97, v103, v204
	v_add_f32_e32 v96, v123, v96
	v_exp_f32_e32 v127, v97
	v_add_f32_e32 v96, v124, v96
	v_add_f32_e32 v96, v125, v96
	v_add_f32_e32 v96, v126, v96
	v_add_f32_e32 v97, v127, v96
	v_sub_f32_e32 v96, v104, v204
	v_exp_f32_e32 v96, v96
	v_sub_f32_e32 v83, v90, v204
	v_exp_f32_e32 v189, v83
	v_sub_f32_e32 v83, v91, v204
	v_add_f32_e32 v98, v96, v97
	v_sub_f32_e32 v97, v105, v204
	v_exp_f32_e32 v97, v97
	v_exp_f32_e32 v191, v83
	v_sub_f32_e32 v83, v92, v204
	v_exp_f32_e32 v193, v83
	v_add_f32_e32 v99, v97, v98
	v_sub_f32_e32 v98, v106, v204
	v_exp_f32_e32 v98, v98
	v_sub_f32_e32 v83, v93, v204
	v_exp_f32_e32 v194, v83
	v_sub_f32_e32 v83, v94, v204
	v_add_f32_e32 v100, v98, v99
	v_sub_f32_e32 v99, v107, v204
	v_exp_f32_e32 v99, v99
	v_exp_f32_e32 v196, v83
	v_sub_f32_e32 v83, v95, v204
	v_exp_f32_e32 v198, v83
	v_add_f32_e32 v101, v99, v100
	v_sub_f32_e32 v100, v108, v204
	v_exp_f32_e32 v100, v100
	v_sub_f32_e32 v64, v64, v204
	v_exp_f32_e32 v177, v64
	v_sub_f32_e32 v65, v65, v204
	v_add_f32_e32 v102, v100, v101
	v_sub_f32_e32 v101, v109, v204
	v_exp_f32_e32 v101, v101
	v_exp_f32_e32 v179, v65
	v_sub_f32_e32 v65, v66, v204
	v_exp_f32_e32 v181, v65
	v_add_f32_e32 v103, v101, v102
	v_sub_f32_e32 v102, v110, v204
	v_exp_f32_e32 v102, v102
	v_sub_f32_e32 v65, v67, v204
	v_exp_f32_e32 v183, v65
	v_sub_f32_e32 v65, v68, v204
	v_add_f32_e32 v104, v102, v103
	v_sub_f32_e32 v103, v111, v204
	v_exp_f32_e32 v103, v103
	v_exp_f32_e32 v186, v65
	v_sub_f32_e32 v65, v69, v204
	v_exp_f32_e32 v188, v65
	v_add_f32_e32 v104, v103, v104
	v_add_f32_e32 v104, v80, v104
	v_add_f32_e32 v104, v81, v104
	v_add_f32_e32 v82, v195, v104
	v_add_f32_e32 v82, v197, v82
	v_add_f32_e32 v82, v199, v82
	v_add_f32_e32 v82, v200, v82
	v_add_f32_e32 v82, v201, v82
	v_add_f32_e32 v82, v202, v82
	v_add_f32_e32 v82, v185, v82
	v_add_f32_e32 v82, v187, v82
	v_add_f32_e32 v82, v189, v82
	v_add_f32_e32 v82, v191, v82
	v_add_f32_e32 v82, v193, v82
	v_add_f32_e32 v82, v194, v82
	v_add_f32_e32 v82, v196, v82
	v_add_f32_e32 v82, v198, v82
	v_add_f32_e32 v64, v177, v82
	v_add_f32_e32 v64, v179, v64
	v_sub_f32_e32 v65, v70, v204
	v_add_f32_e32 v64, v181, v64
	v_exp_f32_e32 v190, v65
	v_sub_f32_e32 v65, v71, v204
	v_add_f32_e32 v64, v183, v64
	v_exp_f32_e32 v192, v65
	v_sub_f32_e32 v65, v72, v204
	v_add_f32_e32 v64, v186, v64
	v_exp_f32_e32 v134, v65
	v_sub_f32_e32 v65, v73, v204
	v_add_f32_e32 v64, v188, v64
	v_exp_f32_e32 v136, v65
	v_sub_f32_e32 v65, v74, v204
	v_add_f32_e32 v64, v190, v64
	v_exp_f32_e32 v138, v65
	v_sub_f32_e32 v65, v75, v204
	v_add_f32_e32 v64, v192, v64
	v_exp_f32_e32 v149, v65
	v_sub_f32_e32 v65, v76, v204
	v_add_f32_e32 v64, v134, v64
	v_exp_f32_e32 v178, v65
	v_sub_f32_e32 v65, v77, v204
	v_add_f32_e32 v64, v136, v64
	v_exp_f32_e32 v180, v65
	v_sub_f32_e32 v65, v78, v204
	v_add_f32_e32 v64, v138, v64
	v_exp_f32_e32 v182, v65
	v_sub_f32_e32 v65, v79, v204
	v_add_f32_e32 v64, v149, v64
	v_exp_f32_e32 v184, v65
	v_sub_f32_e32 v16, v16, v204
	v_add_f32_e32 v64, v178, v64
	v_exp_f32_e32 v110, v16
	v_sub_f32_e32 v17, v17, v204
	v_add_f32_e32 v64, v180, v64
	v_exp_f32_e32 v128, v17
	v_sub_f32_e32 v17, v18, v204
	v_add_f32_e32 v64, v182, v64
	v_exp_f32_e32 v130, v17
	v_sub_f32_e32 v17, v19, v204
	v_add_f32_e32 v64, v184, v64
	v_exp_f32_e32 v132, v17
	v_sub_f32_e32 v17, v20, v204
	v_add_f32_e32 v16, v110, v64
	v_exp_f32_e32 v135, v17
	v_sub_f32_e32 v17, v21, v204
	v_add_f32_e32 v16, v128, v16
	v_exp_f32_e32 v137, v17
	v_sub_f32_e32 v17, v22, v204
	v_add_f32_e32 v16, v130, v16
	v_exp_f32_e32 v139, v17
	v_sub_f32_e32 v17, v23, v204
	v_add_f32_e32 v16, v132, v16
	v_exp_f32_e32 v151, v17
	v_sub_f32_e32 v17, v24, v204
	v_add_f32_e32 v16, v135, v16
	v_exp_f32_e32 v94, v17
	v_sub_f32_e32 v17, v25, v204
	v_add_f32_e32 v16, v137, v16
	v_exp_f32_e32 v104, v17
	v_sub_f32_e32 v17, v26, v204
	v_add_f32_e32 v16, v139, v16
	v_exp_f32_e32 v106, v17
	v_sub_f32_e32 v17, v27, v204
	v_add_f32_e32 v16, v151, v16
	v_exp_f32_e32 v108, v17
	v_sub_f32_e32 v17, v28, v204
	v_add_f32_e32 v16, v94, v16
	v_exp_f32_e32 v111, v17
	v_sub_f32_e32 v17, v29, v204
	v_add_f32_e32 v16, v104, v16
	v_exp_f32_e32 v129, v17
	v_sub_f32_e32 v17, v30, v204
	v_add_f32_e32 v16, v106, v16
	v_exp_f32_e32 v131, v17
	v_sub_f32_e32 v17, v31, v204
	v_add_f32_e32 v16, v108, v16
	v_exp_f32_e32 v133, v17
	v_sub_f32_e32 v0, v0, v204
	v_add_f32_e32 v16, v111, v16
	v_exp_f32_e32 v90, v0
	v_sub_f32_e32 v1, v1, v204
	v_add_f32_e32 v16, v129, v16
	v_exp_f32_e32 v91, v1
	v_sub_f32_e32 v1, v2, v204
	v_add_f32_e32 v16, v131, v16
	v_exp_f32_e32 v92, v1
	v_sub_f32_e32 v1, v3, v204
	v_add_f32_e32 v16, v133, v16
	v_exp_f32_e32 v93, v1
	v_sub_f32_e32 v1, v4, v204
	v_add_f32_e32 v0, v90, v16
	v_exp_f32_e32 v95, v1
	v_sub_f32_e32 v1, v5, v204
	v_add_f32_e32 v0, v91, v0
	v_exp_f32_e32 v105, v1
	v_sub_f32_e32 v1, v6, v204
	v_add_f32_e32 v0, v92, v0
	v_exp_f32_e32 v107, v1
	v_sub_f32_e32 v1, v7, v204
	v_add_f32_e32 v0, v93, v0
	v_exp_f32_e32 v109, v1
	v_sub_f32_e32 v1, v8, v204
	v_add_f32_e32 v0, v95, v0
	v_exp_f32_e32 v82, v1
	v_sub_f32_e32 v1, v9, v204
	v_add_f32_e32 v0, v105, v0
	v_exp_f32_e32 v83, v1
	v_sub_f32_e32 v1, v10, v204
	v_add_f32_e32 v0, v107, v0
	v_exp_f32_e32 v84, v1
	v_sub_f32_e32 v1, v11, v204
	v_add_f32_e32 v0, v109, v0
	v_exp_f32_e32 v85, v1
	v_sub_f32_e32 v1, v12, v204
	v_add_f32_e32 v0, v82, v0
	v_exp_f32_e32 v86, v1
	v_sub_f32_e32 v1, v13, v204
	v_add_f32_e32 v0, v83, v0
	v_exp_f32_e32 v87, v1
	v_sub_f32_e32 v1, v14, v204
	v_add_f32_e32 v0, v84, v0
	v_exp_f32_e32 v88, v1
	v_sub_f32_e32 v1, v15, v204
	v_add_f32_e32 v0, v85, v0
	v_exp_f32_e32 v89, v1
	v_sub_f32_e32 v1, v32, v204
	v_add_f32_e32 v0, v86, v0
	v_exp_f32_e32 v72, v1
	v_sub_f32_e32 v1, v33, v204
	v_add_f32_e32 v0, v87, v0
	v_exp_f32_e32 v73, v1
	v_sub_f32_e32 v1, v34, v204
	v_add_f32_e32 v0, v88, v0
	v_exp_f32_e32 v74, v1
	v_sub_f32_e32 v1, v35, v204
	v_add_f32_e32 v0, v89, v0
	v_exp_f32_e32 v75, v1
	v_sub_f32_e32 v1, v36, v204
	v_add_f32_e32 v0, v72, v0
	v_exp_f32_e32 v76, v1
	v_sub_f32_e32 v1, v37, v204
	v_add_f32_e32 v0, v73, v0
	v_exp_f32_e32 v77, v1
	v_sub_f32_e32 v1, v38, v204
	v_add_f32_e32 v0, v74, v0
	v_exp_f32_e32 v78, v1
	v_sub_f32_e32 v1, v39, v204
	v_add_f32_e32 v0, v75, v0
	v_exp_f32_e32 v79, v1
	v_sub_f32_e32 v1, v40, v204
	v_add_f32_e32 v0, v76, v0
	v_exp_f32_e32 v64, v1
	v_sub_f32_e32 v1, v41, v204
	v_add_f32_e32 v0, v77, v0
	v_exp_f32_e32 v65, v1
	v_sub_f32_e32 v1, v42, v204
	v_add_f32_e32 v0, v78, v0
	v_exp_f32_e32 v66, v1
	v_sub_f32_e32 v1, v43, v204
	v_add_f32_e32 v0, v79, v0
	v_exp_f32_e32 v67, v1
	v_sub_f32_e32 v1, v44, v204
	v_add_f32_e32 v0, v64, v0
	v_exp_f32_e32 v68, v1
	v_sub_f32_e32 v1, v45, v204
	v_add_f32_e32 v0, v65, v0
	v_exp_f32_e32 v69, v1
	v_sub_f32_e32 v1, v46, v204
	v_add_f32_e32 v0, v66, v0
	v_exp_f32_e32 v70, v1
	v_sub_f32_e32 v1, v47, v204
	v_add_f32_e32 v0, v67, v0
	v_exp_f32_e32 v71, v1
	v_sub_f32_e32 v1, v48, v204
	v_add_f32_e32 v0, v68, v0
	v_exp_f32_e32 v42, v1
	v_sub_f32_e32 v1, v49, v204
	v_add_f32_e32 v0, v69, v0
	v_exp_f32_e32 v43, v1
	v_sub_f32_e32 v1, v50, v204
	v_add_f32_e32 v0, v70, v0
	v_exp_f32_e32 v44, v1
	v_sub_f32_e32 v1, v51, v204
	v_add_f32_e32 v0, v71, v0
	v_exp_f32_e32 v45, v1
	v_sub_f32_e32 v1, v52, v204
	v_add_f32_e32 v0, v42, v0
	v_exp_f32_e32 v46, v1
	v_sub_f32_e32 v1, v53, v204
	v_add_f32_e32 v0, v43, v0
	v_exp_f32_e32 v47, v1
	v_sub_f32_e32 v1, v54, v204
	v_add_f32_e32 v0, v44, v0
	v_exp_f32_e32 v48, v1
	v_sub_f32_e32 v1, v55, v204
	v_add_f32_e32 v0, v45, v0
	v_exp_f32_e32 v49, v1
	v_sub_f32_e32 v1, v56, v204
	v_add_f32_e32 v0, v46, v0
	v_exp_f32_e32 v34, v1
	v_sub_f32_e32 v1, v57, v204
	v_add_f32_e32 v0, v47, v0
	v_exp_f32_e32 v35, v1
	v_sub_f32_e32 v1, v58, v204
	v_add_f32_e32 v0, v48, v0
	v_exp_f32_e32 v36, v1
	v_sub_f32_e32 v1, v59, v204
	v_add_f32_e32 v0, v49, v0
	v_exp_f32_e32 v37, v1
	v_sub_f32_e32 v1, v60, v204
	v_add_f32_e32 v0, v34, v0
	v_exp_f32_e32 v38, v1
	v_sub_f32_e32 v1, v61, v204
	v_add_f32_e32 v0, v35, v0
	v_exp_f32_e32 v39, v1
	v_sub_f32_e32 v1, v62, v204
	v_add_f32_e32 v0, v36, v0
	v_exp_f32_e32 v40, v1
	v_sub_f32_e32 v1, v63, v204
	v_add_f32_e32 v0, v37, v0
	v_exp_f32_e32 v41, v1
	v_add_f32_e32 v0, v38, v0
	v_add_f32_e32 v0, v39, v0
	v_add_f32_e32 v0, v40, v0
	v_add_f32_e32 v32, v41, v0
	ds_read2_b64 v[0:3], v172 offset1:2
	ds_read2_b64 v[52:55], v172 offset0:4 offset1:6
	v_cvt_pk_bf16_f32 v16, v203, v205
	v_cvt_pk_bf16_f32 v17, v206, v207
	v_cvt_pk_bf16_f32 v18, v208, v209
	v_cvt_pk_bf16_f32 v19, v210, v211
	v_add_u32_e32 v50, 0x4000, v172
	ds_read2_b64 v[20:23], v50 offset0:32 offset1:34
	s_waitcnt lgkmcnt(2)
	v_mfma_f32_32x32x16_bf16 v[0:15], v[0:3], v[16:19], 0
	v_cvt_pk_bf16_f32 v56, v112, v113
	v_cvt_pk_bf16_f32 v57, v114, v115
	v_cvt_pk_bf16_f32 v58, v116, v117
	v_cvt_pk_bf16_f32 v59, v118, v120
	v_cvt_pk_bf16_f32 v42, v42, v43
	v_cvt_pk_bf16_f32 v43, v44, v45
	v_cvt_pk_bf16_f32 v44, v46, v47
	s_waitcnt lgkmcnt(1)
	v_mfma_f32_32x32x16_bf16 v[0:15], v[52:55], v[56:59], v[0:15]
	ds_read2_b64 v[52:55], v50 offset0:36 offset1:38
	v_cvt_pk_bf16_f32 v45, v48, v49
	ds_read2_b64 v[46:49], v172 offset0:56 offset1:58
	v_cvt_pk_bf16_f32 v34, v34, v35
	v_cvt_pk_bf16_f32 v35, v36, v37
	v_cvt_pk_bf16_f32 v36, v38, v39
	v_cvt_pk_bf16_f32 v37, v40, v41
	s_waitcnt lgkmcnt(2)
	v_mfma_f32_32x32x16_bf16 v[16:31], v[20:23], v[16:19], 0
	ds_read2_b64 v[38:41], v172 offset0:60 offset1:62
	ds_bpermute_b32 v33, v173, v32
	s_waitcnt lgkmcnt(0)
	v_add_f32_e32 v32, v32, v33
	v_mfma_f32_32x32x16_bf16 v[16:31], v[52:55], v[56:59], v[16:31]
	ds_read2_b64 v[56:59], v172 offset0:8 offset1:10
	v_cvt_pk_bf16_f32 v52, v119, v121
	v_cvt_pk_bf16_f32 v53, v122, v123
	v_cvt_pk_bf16_f32 v54, v124, v125
	v_cvt_pk_bf16_f32 v55, v126, v127
	v_div_scale_f32 v33, s[6:7], v32, v32, 1.0
	s_waitcnt lgkmcnt(0)
	v_mfma_f32_32x32x16_bf16 v[0:15], v[56:59], v[52:55], v[0:15]
	ds_read2_b64 v[56:59], v50 offset0:40 offset1:42
	s_mov_b64 s[6:7], 0
	s_waitcnt lgkmcnt(0)
	v_mfma_f32_32x32x16_bf16 v[16:31], v[56:59], v[52:55], v[16:31]
	ds_read2_b64 v[56:59], v172 offset0:12 offset1:14
	v_cvt_pk_bf16_f32 v52, v96, v97
	v_cvt_pk_bf16_f32 v53, v98, v99
	v_cvt_pk_bf16_f32 v54, v100, v101
	v_cvt_pk_bf16_f32 v55, v102, v103
	s_waitcnt lgkmcnt(0)
	s_nop 0
	v_mfma_f32_32x32x16_bf16 v[0:15], v[56:59], v[52:55], v[0:15]
	ds_read2_b64 v[56:59], v50 offset0:44 offset1:46
	s_waitcnt lgkmcnt(0)
	v_mfma_f32_32x32x16_bf16 v[16:31], v[56:59], v[52:55], v[16:31]
	ds_read2_b64 v[56:59], v172 offset0:16 offset1:18
	v_cvt_pk_bf16_f32 v52, v80, v81
	v_cvt_pk_bf16_f32 v53, v195, v197
	v_cvt_pk_bf16_f32 v54, v199, v200
	v_cvt_pk_bf16_f32 v55, v201, v202
	s_waitcnt lgkmcnt(0)
	s_nop 0
	v_mfma_f32_32x32x16_bf16 v[0:15], v[56:59], v[52:55], v[0:15]
	ds_read2_b64 v[56:59], v50 offset0:48 offset1:50
	s_waitcnt lgkmcnt(0)
	v_mfma_f32_32x32x16_bf16 v[16:31], v[56:59], v[52:55], v[16:31]
	ds_read2_b64 v[56:59], v172 offset0:20 offset1:22
	v_cvt_pk_bf16_f32 v52, v185, v187
	v_cvt_pk_bf16_f32 v53, v189, v191
	v_cvt_pk_bf16_f32 v54, v193, v194
	v_cvt_pk_bf16_f32 v55, v196, v198
	s_waitcnt lgkmcnt(0)
	s_nop 0
	v_mfma_f32_32x32x16_bf16 v[0:15], v[56:59], v[52:55], v[0:15]
	ds_read2_b64 v[56:59], v50 offset0:52 offset1:54
	s_waitcnt lgkmcnt(0)
	v_mfma_f32_32x32x16_bf16 v[16:31], v[56:59], v[52:55], v[16:31]
	ds_read2_b64 v[56:59], v172 offset0:24 offset1:26
	v_cvt_pk_bf16_f32 v52, v177, v179
	v_cvt_pk_bf16_f32 v53, v181, v183
	v_cvt_pk_bf16_f32 v54, v186, v188
	v_cvt_pk_bf16_f32 v55, v190, v192
	s_waitcnt lgkmcnt(0)
	s_nop 0
	v_mfma_f32_32x32x16_bf16 v[0:15], v[56:59], v[52:55], v[0:15]
	ds_read2_b64 v[56:59], v50 offset0:56 offset1:58
	s_waitcnt lgkmcnt(0)
	v_mfma_f32_32x32x16_bf16 v[16:31], v[56:59], v[52:55], v[16:31]
	ds_read2_b64 v[56:59], v172 offset0:28 offset1:30
	v_cvt_pk_bf16_f32 v52, v134, v136
	v_cvt_pk_bf16_f32 v53, v138, v149
	v_cvt_pk_bf16_f32 v54, v178, v180
	v_cvt_pk_bf16_f32 v55, v182, v184
	s_waitcnt lgkmcnt(0)
	s_nop 0
	v_mfma_f32_32x32x16_bf16 v[0:15], v[56:59], v[52:55], v[0:15]
	ds_read2_b64 v[56:59], v50 offset0:60 offset1:62
	s_waitcnt lgkmcnt(0)
	v_mfma_f32_32x32x16_bf16 v[16:31], v[56:59], v[52:55], v[16:31]
	ds_read2_b64 v[56:59], v172 offset0:32 offset1:34
	v_cvt_pk_bf16_f32 v52, v110, v128
	v_cvt_pk_bf16_f32 v53, v130, v132
	v_cvt_pk_bf16_f32 v54, v135, v137
	v_cvt_pk_bf16_f32 v55, v139, v151
	v_mov_b32_e32 v151, v161
	s_waitcnt lgkmcnt(0)
	v_mfma_f32_32x32x16_bf16 v[0:15], v[56:59], v[52:55], v[0:15]
	ds_read2_b64 v[56:59], v50 offset0:64 offset1:66
	s_waitcnt lgkmcnt(0)
	v_mfma_f32_32x32x16_bf16 v[16:31], v[56:59], v[52:55], v[16:31]
	ds_read2_b64 v[56:59], v172 offset0:36 offset1:38
	v_cvt_pk_bf16_f32 v52, v94, v104
	v_cvt_pk_bf16_f32 v53, v106, v108
	v_cvt_pk_bf16_f32 v54, v111, v129
	v_cvt_pk_bf16_f32 v55, v131, v133
	s_waitcnt lgkmcnt(0)
	s_nop 0
	v_mfma_f32_32x32x16_bf16 v[0:15], v[56:59], v[52:55], v[0:15]
	ds_read2_b64 v[56:59], v50 offset0:68 offset1:70
	s_waitcnt lgkmcnt(0)
	v_mfma_f32_32x32x16_bf16 v[16:31], v[56:59], v[52:55], v[16:31]
	ds_read2_b64 v[56:59], v172 offset0:40 offset1:42
	v_cvt_pk_bf16_f32 v52, v90, v91
	v_cvt_pk_bf16_f32 v53, v92, v93
	v_cvt_pk_bf16_f32 v54, v95, v105
	v_cvt_pk_bf16_f32 v55, v107, v109
	s_waitcnt lgkmcnt(0)
	s_nop 0
	v_mfma_f32_32x32x16_bf16 v[0:15], v[56:59], v[52:55], v[0:15]
	ds_read2_b64 v[56:59], v50 offset0:72 offset1:74
	s_waitcnt lgkmcnt(0)
	v_mfma_f32_32x32x16_bf16 v[16:31], v[56:59], v[52:55], v[16:31]
	ds_read2_b64 v[56:59], v172 offset0:44 offset1:46
	v_cvt_pk_bf16_f32 v52, v82, v83
	v_cvt_pk_bf16_f32 v53, v84, v85
	v_cvt_pk_bf16_f32 v54, v86, v87
	v_cvt_pk_bf16_f32 v55, v88, v89
	s_waitcnt lgkmcnt(0)
	s_nop 0
	v_mfma_f32_32x32x16_bf16 v[0:15], v[56:59], v[52:55], v[0:15]
	ds_read2_b64 v[56:59], v50 offset0:76 offset1:78
	s_waitcnt lgkmcnt(0)
	v_mfma_f32_32x32x16_bf16 v[16:31], v[56:59], v[52:55], v[16:31]
	ds_read2_b64 v[56:59], v172 offset0:48 offset1:50
	v_cvt_pk_bf16_f32 v52, v72, v73
	v_cvt_pk_bf16_f32 v53, v74, v75
	v_cvt_pk_bf16_f32 v54, v76, v77
	v_cvt_pk_bf16_f32 v55, v78, v79
	s_waitcnt lgkmcnt(0)
	s_nop 0
	v_mfma_f32_32x32x16_bf16 v[0:15], v[56:59], v[52:55], v[0:15]
	ds_read2_b64 v[56:59], v50 offset0:80 offset1:82
	s_waitcnt lgkmcnt(0)
	v_mfma_f32_32x32x16_bf16 v[16:31], v[56:59], v[52:55], v[16:31]
	ds_read2_b64 v[56:59], v172 offset0:52 offset1:54
	v_cvt_pk_bf16_f32 v52, v64, v65
	v_cvt_pk_bf16_f32 v53, v66, v67
	v_cvt_pk_bf16_f32 v54, v68, v69
	v_cvt_pk_bf16_f32 v55, v70, v71
	s_waitcnt lgkmcnt(0)
	s_nop 0
	v_mfma_f32_32x32x16_bf16 v[0:15], v[56:59], v[52:55], v[0:15]
	ds_read2_b64 v[56:59], v50 offset0:84 offset1:86
	v_mfma_f32_32x32x16_bf16 v[0:15], v[46:49], v[42:45], v[0:15]
	ds_read2_b64 v[46:49], v50 offset0:88 offset1:90
	s_waitcnt lgkmcnt(1)
	v_mfma_f32_32x32x16_bf16 v[16:31], v[56:59], v[52:55], v[16:31]
	v_mfma_f32_32x32x16_bf16 v[0:15], v[38:41], v[34:37], v[0:15]
	ds_read2_b64 v[38:41], v50 offset0:92 offset1:94
	s_waitcnt lgkmcnt(1)
	v_mfma_f32_32x32x16_bf16 v[16:31], v[46:49], v[42:45], v[16:31]
	s_waitcnt lgkmcnt(0)
	v_mfma_f32_32x32x16_bf16 v[16:31], v[38:41], v[34:37], v[16:31]
	v_rcp_f32_e32 v34, v33
	s_nop 0
	v_fma_f32 v35, -v33, v34, 1.0
	v_fmac_f32_e32 v34, v35, v34
	v_div_scale_f32 v35, vcc, 1.0, v32, 1.0
	v_mul_f32_e32 v36, v35, v34
	v_fma_f32 v37, -v33, v36, v35
	v_fmac_f32_e32 v36, v37, v34
	v_fma_f32 v33, -v33, v36, v35
	v_div_fmas_f32 v33, v33, v34, v36
	v_div_fixup_f32 v32, v33, v32, 1.0
	v_lshl_add_u64 v[34:35], s[20:21], 0, v[152:153]
	v_lshl_add_u64 v[34:35], v[34:35], 0, s[4:5]
	v_pk_mul_f32 v[0:1], v[0:1], v[32:33] op_sel_hi:[1,0]
	v_pk_mul_f32 v[2:3], v[2:3], v[32:33] op_sel_hi:[1,0]
	v_lshl_add_u64 v[34:35], v[34:35], 0, v[150:151]
	v_cvt_pk_bf16_f32 v0, v0, v1
	v_cvt_pk_bf16_f32 v1, v2, v3
	global_store_dwordx2 v[34:35], v[0:1], off offset:1536
	v_pk_mul_f32 v[0:1], v[4:5], v[32:33] op_sel_hi:[1,0]
	v_pk_mul_f32 v[2:3], v[6:7], v[32:33] op_sel_hi:[1,0]
	v_cvt_pk_bf16_f32 v0, v0, v1
	v_cvt_pk_bf16_f32 v1, v2, v3
	global_store_dwordx2 v[34:35], v[0:1], off offset:1552
	v_pk_mul_f32 v[0:1], v[8:9], v[32:33] op_sel_hi:[1,0]
	v_pk_mul_f32 v[2:3], v[10:11], v[32:33] op_sel_hi:[1,0]
	v_cvt_pk_bf16_f32 v0, v0, v1
	v_cvt_pk_bf16_f32 v1, v2, v3
	global_store_dwordx2 v[34:35], v[0:1], off offset:1568
	v_pk_mul_f32 v[0:1], v[12:13], v[32:33] op_sel_hi:[1,0]
	v_pk_mul_f32 v[2:3], v[14:15], v[32:33] op_sel_hi:[1,0]
	v_cvt_pk_bf16_f32 v0, v0, v1
	v_cvt_pk_bf16_f32 v1, v2, v3
	global_store_dwordx2 v[34:35], v[0:1], off offset:1584
	v_pk_mul_f32 v[0:1], v[16:17], v[32:33] op_sel_hi:[1,0]
	v_pk_mul_f32 v[2:3], v[18:19], v[32:33] op_sel_hi:[1,0]
	v_cvt_pk_bf16_f32 v0, v0, v1
	v_cvt_pk_bf16_f32 v1, v2, v3
	global_store_dwordx2 v[34:35], v[0:1], off offset:1600
	v_pk_mul_f32 v[0:1], v[20:21], v[32:33] op_sel_hi:[1,0]
	v_pk_mul_f32 v[2:3], v[22:23], v[32:33] op_sel_hi:[1,0]
	v_cvt_pk_bf16_f32 v0, v0, v1
	v_cvt_pk_bf16_f32 v1, v2, v3
	global_store_dwordx2 v[34:35], v[0:1], off offset:1616
	v_pk_mul_f32 v[0:1], v[24:25], v[32:33] op_sel_hi:[1,0]
	v_pk_mul_f32 v[2:3], v[26:27], v[32:33] op_sel_hi:[1,0]
	v_cvt_pk_bf16_f32 v0, v0, v1
	v_cvt_pk_bf16_f32 v1, v2, v3
	global_store_dwordx2 v[34:35], v[0:1], off offset:1632
	v_pk_mul_f32 v[0:1], v[28:29], v[32:33] op_sel_hi:[1,0]
	v_pk_mul_f32 v[2:3], v[30:31], v[32:33] op_sel_hi:[1,0]
	v_cvt_pk_bf16_f32 v0, v0, v1
	v_cvt_pk_bf16_f32 v1, v2, v3
	global_store_dwordx2 v[34:35], v[0:1], off offset:1648
	s_barrier
	s_branch .LBB0_225
